# conv d-loop software-pipelined: next iteration's LDS fragments read during the current MFMAs, two shared A fragments reused (8 instead of 10 reads)
# speedup vs baseline: 1.0019x; 1.0019x over previous
.LBB0_985:
	v_add_u32_e32 v1, s6, v43
	v_cmp_gt_i32_e64 s[36:37], s82, v1
	s_or_b64 s[40:41], s[40:41], exec
	s_and_saveexec_b64 s[42:43], s[36:37]
	s_cbranch_execz .LBB0_984
	v_or_b32_e32 v0, v1, v44
	v_ashrrev_i32_e32 v54, s83, v0
	v_ashrrev_i32_e32 v0, s83, v1
	v_or_b32_e32 v2, 31, v1
	v_subrev_u32_e32 v0, s80, v0
	v_add_u32_e32 v0, 1, v0
	v_bitop3_b32 v35, v1, s84, v44 bitop3:0xc8
	v_ashrrev_i32_e32 v1, s83, v2
	v_max_i32_e32 v0, s85, v0
	v_min_i32_e32 v36, s81, v1
	v_mul_lo_u32 v1, v35, s79
	v_cmp_le_i32_e64 s[36:37], v0, v36
	v_add_u32_e32 v55, s24, v1
	v_lshlrev_b32_e32 v34, 6, v54
	s_and_saveexec_b64 s[6:7], s[36:37]
	s_xor_b64 s[46:47], exec, s[6:7]
	s_cbranch_execz .LBB0_990
	v_add_u32_e32 v37, -1, v0
	v_lshlrev_b32_e32 v1, 7, v0
	v_sub_u32_e32 v39, v54, v0
	v_lshlrev_b32_e32 v34, 6, v54
	v_lshlrev_b32_e32 v0, 6, v0
	v_mov_b32_e32 v16, 0
	v_sub_u32_e32 v38, v53, v1
	v_sub_u32_e32 v40, v34, v0
	s_mov_b64 s[50:51], 0
	v_mov_b32_e32 v17, v16
	v_mov_b32_e32 v18, v16
	v_mov_b32_e32 v19, v16
	v_mov_b32_e32 v20, v16
	v_mov_b32_e32 v21, v16
	v_mov_b32_e32 v22, v16
	v_mov_b32_e32 v23, v16
	v_mov_b32_e32 v24, v16
	v_mov_b32_e32 v25, v16
	v_mov_b32_e32 v26, v16
	v_mov_b32_e32 v27, v16
	v_mov_b32_e32 v28, v16
	v_mov_b32_e32 v29, v16
	v_mov_b32_e32 v30, v16
	v_mov_b32_e32 v31, v16
	v_mov_b32_e32 v0, v16
	v_mov_b32_e32 v1, v16
	v_mov_b32_e32 v2, v16
	v_mov_b32_e32 v3, v16
	v_mov_b32_e32 v4, v16
	v_mov_b32_e32 v5, v16
	v_mov_b32_e32 v6, v16
	v_mov_b32_e32 v7, v16
	v_mov_b32_e32 v8, v16
	v_mov_b32_e32 v9, v16
	v_mov_b32_e32 v10, v16
	v_mov_b32_e32 v11, v16
	v_mov_b32_e32 v12, v16
	v_mov_b32_e32 v13, v16
	v_mov_b32_e32 v14, v16
	v_mov_b32_e32 v15, v16
	v_cmp_lt_i32_e64 s[36:37], -1, v39
	v_cmp_gt_i32_e64 s[100:101], s80, v39
	s_nop 1
	s_and_b64 s[36:37], s[36:37], s[100:101]
	v_cndmask_b32_e64 v41, 0, v40, s[36:37]
	v_or_b32_e32 v41, v41, v45
	v_lshl_add_u32 v41, v41, 1, v55
	ds_read_b128 v[76:79], v38
	ds_read_b128 v[80:83], v38 offset:32
	ds_read_b128 v[84:87], v38 offset:64
	ds_read_b128 v[88:91], v38 offset:96
	ds_read_b128 v[108:111], v38 offset:128
	ds_read_b128 v[112:115], v38 offset:160
	ds_read_b128 v[92:95], v41
	ds_read_b128 v[96:99], v41 offset:32
	ds_read_b128 v[100:103], v41 offset:64
	ds_read_b128 v[104:107], v41 offset:96
.Lconv_dloop_0:
	v_add_u32_e32 v38, 0xffffff80, v38
	v_add_u32_e32 v39, -1, v39
	v_subrev_u32_e32 v40, 64, v40
	v_add_u32_e32 v37, 1, v37
	v_max_i32_e32 v140, 0, v38
	v_cmp_lt_i32_e64 s[38:39], -1, v39
	v_cmp_gt_i32_e64 s[100:101], s80, v39
	s_nop 1
	s_and_b64 s[38:39], s[38:39], s[100:101]
	v_cndmask_b32_e64 v41, 0, v40, s[38:39]
	v_or_b32_e32 v41, v41, v45
	v_lshl_add_u32 v41, v41, 1, v55
	ds_read_b128 v[124:127], v41
	ds_read_b128 v[128:131], v41 offset:32
	ds_read_b128 v[132:135], v41 offset:64
	ds_read_b128 v[136:139], v41 offset:96
	ds_read_b128 v[116:119], v140 offset:64
	ds_read_b128 v[120:123], v140 offset:96
	s_waitcnt lgkmcnt(6)
	v_cndmask_b32_e64 v92, 0, v92, s[36:37]
	v_cndmask_b32_e64 v93, 0, v93, s[36:37]
	v_cndmask_b32_e64 v94, 0, v94, s[36:37]
	v_cndmask_b32_e64 v95, 0, v95, s[36:37]
	v_cndmask_b32_e64 v96, 0, v96, s[36:37]
	v_cndmask_b32_e64 v97, 0, v97, s[36:37]
	v_cndmask_b32_e64 v98, 0, v98, s[36:37]
	v_cndmask_b32_e64 v99, 0, v99, s[36:37]
	v_cndmask_b32_e64 v100, 0, v100, s[36:37]
	v_cndmask_b32_e64 v101, 0, v101, s[36:37]
	v_cndmask_b32_e64 v102, 0, v102, s[36:37]
	v_cndmask_b32_e64 v103, 0, v103, s[36:37]
	v_cndmask_b32_e64 v104, 0, v104, s[36:37]
	v_cndmask_b32_e64 v105, 0, v105, s[36:37]
	v_cndmask_b32_e64 v106, 0, v106, s[36:37]
	v_cndmask_b32_e64 v107, 0, v107, s[36:37]
	v_mfma_f32_32x32x16_bf16 v[16:31], v[108:111], v[100:103], v[16:31]
	v_mfma_f32_32x32x16_bf16 v[0:15], v[76:79], v[92:95], v[0:15]
	ds_read_b128 v[108:111], v140
	v_mfma_f32_32x32x16_bf16 v[16:31], v[112:115], v[104:107], v[16:31]
	v_mfma_f32_32x32x16_bf16 v[0:15], v[80:83], v[96:99], v[0:15]
	ds_read_b128 v[112:115], v140 offset:32
	v_mfma_f32_32x32x16_bf16 v[16:31], v[84:87], v[92:95], v[16:31]
	v_mfma_f32_32x32x16_bf16 v[0:15], v[84:87], v[100:103], v[0:15]
	v_mfma_f32_32x32x16_bf16 v[16:31], v[88:91], v[96:99], v[16:31]
	v_mfma_f32_32x32x16_bf16 v[0:15], v[88:91], v[104:107], v[0:15]
	v_cmp_ge_i32_e64 s[100:101], v37, v36
	s_nop 1
	s_or_b64 s[50:51], s[100:101], s[50:51]
	s_andn2_b64 exec, exec, s[50:51]
	s_cbranch_execz .Lconv_ddone_0
	v_add_u32_e32 v38, 0xffffff80, v38
	v_add_u32_e32 v39, -1, v39
	v_subrev_u32_e32 v40, 64, v40
	v_add_u32_e32 v37, 1, v37
	v_max_i32_e32 v140, 0, v38
	v_cmp_lt_i32_e64 s[36:37], -1, v39
	v_cmp_gt_i32_e64 s[100:101], s80, v39
	s_nop 1
	s_and_b64 s[36:37], s[36:37], s[100:101]
	v_cndmask_b32_e64 v41, 0, v40, s[36:37]
	v_or_b32_e32 v41, v41, v45
	v_lshl_add_u32 v41, v41, 1, v55
	ds_read_b128 v[92:95], v41
	ds_read_b128 v[96:99], v41 offset:32
	ds_read_b128 v[100:103], v41 offset:64
	ds_read_b128 v[104:107], v41 offset:96
	ds_read_b128 v[84:87], v140 offset:64
	ds_read_b128 v[88:91], v140 offset:96
	s_waitcnt lgkmcnt(6)
	v_cndmask_b32_e64 v124, 0, v124, s[38:39]
	v_cndmask_b32_e64 v125, 0, v125, s[38:39]
	v_cndmask_b32_e64 v126, 0, v126, s[38:39]
	v_cndmask_b32_e64 v127, 0, v127, s[38:39]
	v_cndmask_b32_e64 v128, 0, v128, s[38:39]
	v_cndmask_b32_e64 v129, 0, v129, s[38:39]
	v_cndmask_b32_e64 v130, 0, v130, s[38:39]
	v_cndmask_b32_e64 v131, 0, v131, s[38:39]
	v_cndmask_b32_e64 v132, 0, v132, s[38:39]
	v_cndmask_b32_e64 v133, 0, v133, s[38:39]
	v_cndmask_b32_e64 v134, 0, v134, s[38:39]
	v_cndmask_b32_e64 v135, 0, v135, s[38:39]
	v_cndmask_b32_e64 v136, 0, v136, s[38:39]
	v_cndmask_b32_e64 v137, 0, v137, s[38:39]
	v_cndmask_b32_e64 v138, 0, v138, s[38:39]
	v_cndmask_b32_e64 v139, 0, v139, s[38:39]
	v_mfma_f32_32x32x16_bf16 v[16:31], v[76:79], v[132:135], v[16:31]
	v_mfma_f32_32x32x16_bf16 v[0:15], v[108:111], v[124:127], v[0:15]
	ds_read_b128 v[76:79], v140
	v_mfma_f32_32x32x16_bf16 v[16:31], v[80:83], v[136:139], v[16:31]
	v_mfma_f32_32x32x16_bf16 v[0:15], v[112:115], v[128:131], v[0:15]
	ds_read_b128 v[80:83], v140 offset:32
	v_mfma_f32_32x32x16_bf16 v[16:31], v[116:119], v[124:127], v[16:31]
	v_mfma_f32_32x32x16_bf16 v[0:15], v[116:119], v[132:135], v[0:15]
	v_mfma_f32_32x32x16_bf16 v[16:31], v[120:123], v[128:131], v[16:31]
	v_mfma_f32_32x32x16_bf16 v[0:15], v[120:123], v[136:139], v[0:15]
	v_cmp_ge_i32_e64 s[100:101], v37, v36
	s_nop 1
	s_or_b64 s[50:51], s[100:101], s[50:51]
	s_andn2_b64 exec, exec, s[50:51]
	s_cbranch_execnz .Lconv_dloop_0
.Lconv_ddone_0:
	s_or_b64 exec, exec, s[50:51]

.LBB0_1099:
	v_add_u32_e32 v1, s6, v45
	v_cmp_gt_i32_e64 s[34:35], s77, v1
	s_or_b64 s[38:39], s[38:39], exec
	s_and_saveexec_b64 s[40:41], s[34:35]
	s_cbranch_execz .LBB0_1098
	v_or_b32_e32 v0, v1, v46
	v_ashrrev_i32_e32 v56, s78, v0
	v_ashrrev_i32_e32 v0, s78, v1
	v_or_b32_e32 v2, 31, v1
	v_subrev_u32_e32 v0, s65, v0
	v_add_u32_e32 v0, 1, v0
	v_bitop3_b32 v37, v1, s79, v46 bitop3:0xc8
	v_ashrrev_i32_e32 v1, s78, v2
	v_max_i32_e32 v0, s80, v0
	v_min_i32_e32 v38, s76, v1
	v_mul_lo_u32 v1, v37, s61
	v_cmp_le_i32_e64 s[34:35], v0, v38
	v_add_u32_e32 v57, s24, v1
	v_lshlrev_b32_e32 v36, 6, v56
	s_and_saveexec_b64 s[6:7], s[34:35]
	s_xor_b64 s[44:45], exec, s[6:7]
	s_cbranch_execz .LBB0_1104
	v_add_u32_e32 v39, -1, v0
	v_lshlrev_b32_e32 v1, 7, v0
	v_sub_u32_e32 v41, v56, v0
	v_lshlrev_b32_e32 v36, 6, v56
	v_lshlrev_b32_e32 v0, 6, v0
	v_mov_b32_e32 v16, 0
	v_sub_u32_e32 v40, v55, v1
	v_sub_u32_e32 v42, v36, v0
	s_mov_b64 s[46:47], 0
	v_mov_b32_e32 v17, v16
	v_mov_b32_e32 v18, v16
	v_mov_b32_e32 v19, v16
	v_mov_b32_e32 v20, v16
	v_mov_b32_e32 v21, v16
	v_mov_b32_e32 v22, v16
	v_mov_b32_e32 v23, v16
	v_mov_b32_e32 v24, v16
	v_mov_b32_e32 v25, v16
	v_mov_b32_e32 v26, v16
	v_mov_b32_e32 v27, v16
	v_mov_b32_e32 v28, v16
	v_mov_b32_e32 v29, v16
	v_mov_b32_e32 v30, v16
	v_mov_b32_e32 v31, v16
	v_mov_b32_e32 v0, v16
	v_mov_b32_e32 v1, v16
	v_mov_b32_e32 v2, v16
	v_mov_b32_e32 v3, v16
	v_mov_b32_e32 v4, v16
	v_mov_b32_e32 v5, v16
	v_mov_b32_e32 v6, v16
	v_mov_b32_e32 v7, v16
	v_mov_b32_e32 v8, v16
	v_mov_b32_e32 v9, v16
	v_mov_b32_e32 v10, v16
	v_mov_b32_e32 v11, v16
	v_mov_b32_e32 v12, v16
	v_mov_b32_e32 v13, v16
	v_mov_b32_e32 v14, v16
	v_mov_b32_e32 v15, v16
	v_cmp_lt_i32_e64 s[34:35], -1, v41
	v_cmp_gt_i32_e64 s[100:101], s65, v41
	s_nop 1
	s_and_b64 s[34:35], s[34:35], s[100:101]
	v_cndmask_b32_e64 v43, 0, v42, s[34:35]
	v_or_b32_e32 v43, v43, v47
	v_lshl_add_u32 v43, v43, 1, v57
	ds_read_b128 v[76:79], v40
	ds_read_b128 v[80:83], v40 offset:32
	ds_read_b128 v[84:87], v40 offset:64
	ds_read_b128 v[88:91], v40 offset:96
	ds_read_b128 v[108:111], v40 offset:128
	ds_read_b128 v[112:115], v40 offset:160
	ds_read_b128 v[92:95], v43
	ds_read_b128 v[96:99], v43 offset:32
	ds_read_b128 v[100:103], v43 offset:64
	ds_read_b128 v[104:107], v43 offset:96
.Lconv_dloop_1:
	v_add_u32_e32 v40, 0xffffff80, v40
	v_add_u32_e32 v41, -1, v41
	v_subrev_u32_e32 v42, 64, v42
	v_add_u32_e32 v39, 1, v39
	v_max_i32_e32 v140, 0, v40
	v_cmp_lt_i32_e64 s[36:37], -1, v41
	v_cmp_gt_i32_e64 s[100:101], s65, v41
	s_nop 1
	s_and_b64 s[36:37], s[36:37], s[100:101]
	v_cndmask_b32_e64 v43, 0, v42, s[36:37]
	v_or_b32_e32 v43, v43, v47
	v_lshl_add_u32 v43, v43, 1, v57
	ds_read_b128 v[124:127], v43
	ds_read_b128 v[128:131], v43 offset:32
	ds_read_b128 v[132:135], v43 offset:64
	ds_read_b128 v[136:139], v43 offset:96
	ds_read_b128 v[116:119], v140 offset:64
	ds_read_b128 v[120:123], v140 offset:96
	s_waitcnt lgkmcnt(6)
	v_cndmask_b32_e64 v92, 0, v92, s[34:35]
	v_cndmask_b32_e64 v93, 0, v93, s[34:35]
	v_cndmask_b32_e64 v94, 0, v94, s[34:35]
	v_cndmask_b32_e64 v95, 0, v95, s[34:35]
	v_cndmask_b32_e64 v96, 0, v96, s[34:35]
	v_cndmask_b32_e64 v97, 0, v97, s[34:35]
	v_cndmask_b32_e64 v98, 0, v98, s[34:35]
	v_cndmask_b32_e64 v99, 0, v99, s[34:35]
	v_cndmask_b32_e64 v100, 0, v100, s[34:35]
	v_cndmask_b32_e64 v101, 0, v101, s[34:35]
	v_cndmask_b32_e64 v102, 0, v102, s[34:35]
	v_cndmask_b32_e64 v103, 0, v103, s[34:35]
	v_cndmask_b32_e64 v104, 0, v104, s[34:35]
	v_cndmask_b32_e64 v105, 0, v105, s[34:35]
	v_cndmask_b32_e64 v106, 0, v106, s[34:35]
	v_cndmask_b32_e64 v107, 0, v107, s[34:35]
	v_mfma_f32_32x32x16_bf16 v[16:31], v[108:111], v[100:103], v[16:31]
	v_mfma_f32_32x32x16_bf16 v[0:15], v[76:79], v[92:95], v[0:15]
	ds_read_b128 v[108:111], v140
	v_mfma_f32_32x32x16_bf16 v[16:31], v[112:115], v[104:107], v[16:31]
	v_mfma_f32_32x32x16_bf16 v[0:15], v[80:83], v[96:99], v[0:15]
	ds_read_b128 v[112:115], v140 offset:32
	v_mfma_f32_32x32x16_bf16 v[16:31], v[84:87], v[92:95], v[16:31]
	v_mfma_f32_32x32x16_bf16 v[0:15], v[84:87], v[100:103], v[0:15]
	v_mfma_f32_32x32x16_bf16 v[16:31], v[88:91], v[96:99], v[16:31]
	v_mfma_f32_32x32x16_bf16 v[0:15], v[88:91], v[104:107], v[0:15]
	v_cmp_ge_i32_e64 s[100:101], v39, v38
	s_nop 1
	s_or_b64 s[46:47], s[100:101], s[46:47]
	s_andn2_b64 exec, exec, s[46:47]
	s_cbranch_execz .Lconv_ddone_1
	v_add_u32_e32 v40, 0xffffff80, v40
	v_add_u32_e32 v41, -1, v41
	v_subrev_u32_e32 v42, 64, v42
	v_add_u32_e32 v39, 1, v39
	v_max_i32_e32 v140, 0, v40
	v_cmp_lt_i32_e64 s[34:35], -1, v41
	v_cmp_gt_i32_e64 s[100:101], s65, v41
	s_nop 1
	s_and_b64 s[34:35], s[34:35], s[100:101]
	v_cndmask_b32_e64 v43, 0, v42, s[34:35]
	v_or_b32_e32 v43, v43, v47
	v_lshl_add_u32 v43, v43, 1, v57
	ds_read_b128 v[92:95], v43
	ds_read_b128 v[96:99], v43 offset:32
	ds_read_b128 v[100:103], v43 offset:64
	ds_read_b128 v[104:107], v43 offset:96
	ds_read_b128 v[84:87], v140 offset:64
	ds_read_b128 v[88:91], v140 offset:96
	s_waitcnt lgkmcnt(6)
	v_cndmask_b32_e64 v124, 0, v124, s[36:37]
	v_cndmask_b32_e64 v125, 0, v125, s[36:37]
	v_cndmask_b32_e64 v126, 0, v126, s[36:37]
	v_cndmask_b32_e64 v127, 0, v127, s[36:37]
	v_cndmask_b32_e64 v128, 0, v128, s[36:37]
	v_cndmask_b32_e64 v129, 0, v129, s[36:37]
	v_cndmask_b32_e64 v130, 0, v130, s[36:37]
	v_cndmask_b32_e64 v131, 0, v131, s[36:37]
	v_cndmask_b32_e64 v132, 0, v132, s[36:37]
	v_cndmask_b32_e64 v133, 0, v133, s[36:37]
	v_cndmask_b32_e64 v134, 0, v134, s[36:37]
	v_cndmask_b32_e64 v135, 0, v135, s[36:37]
	v_cndmask_b32_e64 v136, 0, v136, s[36:37]
	v_cndmask_b32_e64 v137, 0, v137, s[36:37]
	v_cndmask_b32_e64 v138, 0, v138, s[36:37]
	v_cndmask_b32_e64 v139, 0, v139, s[36:37]
	v_mfma_f32_32x32x16_bf16 v[16:31], v[76:79], v[132:135], v[16:31]
	v_mfma_f32_32x32x16_bf16 v[0:15], v[108:111], v[124:127], v[0:15]
	ds_read_b128 v[76:79], v140
	v_mfma_f32_32x32x16_bf16 v[16:31], v[80:83], v[136:139], v[16:31]
	v_mfma_f32_32x32x16_bf16 v[0:15], v[112:115], v[128:131], v[0:15]
	ds_read_b128 v[80:83], v140 offset:32
	v_mfma_f32_32x32x16_bf16 v[16:31], v[116:119], v[124:127], v[16:31]
	v_mfma_f32_32x32x16_bf16 v[0:15], v[116:119], v[132:135], v[0:15]
	v_mfma_f32_32x32x16_bf16 v[16:31], v[120:123], v[128:131], v[16:31]
	v_mfma_f32_32x32x16_bf16 v[0:15], v[120:123], v[136:139], v[0:15]
	v_cmp_ge_i32_e64 s[100:101], v39, v38
	s_nop 1
	s_or_b64 s[46:47], s[100:101], s[46:47]
	s_andn2_b64 exec, exec, s[46:47]
	s_cbranch_execnz .Lconv_dloop_1
.Lconv_ddone_1:
	s_or_b64 exec, exec, s[46:47]
